# attention loop: packed v_pk_add/mul/fma_f32 split into scalar pairs (lever 7.5), on top of v19
# speedup vs baseline: 1.0049x; 1.0005x over previous
.LBB0_157:
	v_max_f32_e32 v0, v177, v177
	s_nop 1
	v_max_f32_e32 v136, v176, v176
	v_max_f32_e32 v0, v136, v0
	v_max_f32_e32 v136, v179, v179
	v_max_f32_e32 v137, v178, v178
	v_max_f32_e32 v136, v137, v136
	v_max_f32_e32 v137, v183, v183
	v_max_f32_e32 v138, v182, v182
	v_max_f32_e32 v137, v138, v137
	v_max3_f32 v137, v180, v181, v137
	v_max3_f32 v0, v0, v136, v137
	ds_bpermute_b32 v136, v199, v0
	v_max_f32_e32 v138, v168, v168
	v_max_f32_e32 v139, v170, v170
	v_max_f32_e32 v200, v166, v166
	v_max_f32_e32 v203, v146, v146
	s_waitcnt lgkmcnt(0)
	v_max_f32_e32 v136, v136, v136
	v_max_f32_e32 v0, v0, v136
	ds_bpermute_b32 v136, v195, v0
	v_max_f32_e32 v212, v134, v134
	s_add_i32 s45, s38, 2
	s_cmp_ge_u32 s45, s36
	s_cselect_b64 s[96:97], -1, 0
	s_waitcnt lgkmcnt(0)
	v_max3_f32 v206, v194, v0, v136
	v_sub_f32_e32 v136, v176, v206
	v_sub_f32_e32 v137, v177, v206
	v_sub_f32_e32 v0, v194, v206
	v_exp_f32_e32 v176, v136
	v_exp_f32_e32 v177, v137
	v_sub_f32_e32 v136, v178, v206
	v_sub_f32_e32 v137, v179, v206
	v_exp_f32_e32 v194, v0
	v_exp_f32_e32 v178, v136
	v_exp_f32_e32 v179, v137
	v_sub_f32_e32 v136, v180, v206
	v_sub_f32_e32 v137, v181, v206
	v_mul_f32_e32 v130, v130, v194
	v_mul_f32_e32 v131, v131, v194
	v_exp_f32_e32 v180, v136
	v_exp_f32_e32 v181, v137
	v_sub_f32_e32 v136, v182, v206
	v_sub_f32_e32 v137, v183, v206
	v_max_f32_e32 v183, v174, v174
	v_exp_f32_e32 v182, v136
	v_max_f32_e32 v136, v169, v169
	v_max_f32_e32 v136, v138, v136
	v_max_f32_e32 v138, v171, v171
	v_max_f32_e32 v138, v139, v138
	v_max_f32_e32 v139, v175, v175
	v_max_f32_e32 v139, v183, v139
	v_max3_f32 v139, v172, v173, v139
	v_max3_f32 v138, v136, v138, v139
	ds_bpermute_b32 v139, v199, v138
	v_mul_f32_e32 v128, v128, v194
	v_mul_f32_e32 v129, v129, v194
	v_exp_f32_e32 v183, v137
	v_cvt_pk_bf16_f32 v136, v176, v177
	v_cvt_pk_bf16_f32 v137, v178, v179
	s_waitcnt lgkmcnt(0)
	v_max_f32_e32 v0, v139, v139
	v_max_f32_e32 v0, v138, v0
	ds_bpermute_b32 v197, v195, v0
	v_cvt_pk_bf16_f32 v138, v180, v181
	v_cvt_pk_bf16_f32 v139, v182, v183
	s_cmp_lt_u32 s45, s36
	s_nop 0
	v_mfma_f32_16x16x32_bf16 v[128:131], v[84:87], v[136:139], v[128:131]
	s_waitcnt lgkmcnt(0)
	v_max3_f32 v204, v196, v0, v197
	v_sub_f32_e32 v0, v196, v204
	v_max_f32_e32 v196, v165, v165
	v_max_f32_e32 v197, v164, v164
	v_max_f32_e32 v196, v197, v196
	v_max_f32_e32 v197, v167, v167
	v_max_f32_e32 v197, v200, v197
	v_max_f32_e32 v200, v147, v147
	v_max_f32_e32 v200, v203, v200
	v_max3_f32 v200, v144, v145, v200
	v_max3_f32 v197, v196, v197, v200
	ds_bpermute_b32 v200, v199, v197
	v_exp_f32_e32 v196, v0
	v_max_f32_e32 v203, v142, v142
	v_sub_f32_e32 v168, v168, v204
	v_sub_f32_e32 v169, v169, v204
	v_sub_f32_e32 v170, v170, v204
	v_sub_f32_e32 v171, v171, v204
	s_waitcnt lgkmcnt(0)
	v_max_f32_e32 v0, v200, v200
	v_max_f32_e32 v0, v197, v0
	ds_bpermute_b32 v197, v195, v0
	v_sub_f32_e32 v172, v172, v204
	v_sub_f32_e32 v173, v173, v204
	v_sub_f32_e32 v174, v174, v204
	v_sub_f32_e32 v175, v175, v204
	v_exp_f32_e32 v168, v168
	v_exp_f32_e32 v169, v169
	s_waitcnt lgkmcnt(0)
	v_max3_f32 v200, v198, v0, v197
	v_mul_f32_e32 v98, v98, v196
	v_mul_f32_e32 v99, v99, v196
	v_mul_f32_e32 v96, v96, v196
	v_mul_f32_e32 v97, v97, v196
	v_sub_f32_e32 v0, v198, v200
	v_max_f32_e32 v197, v141, v141
	v_max_f32_e32 v198, v140, v140
	v_max_f32_e32 v197, v198, v197
	v_max_f32_e32 v198, v143, v143
	v_max_f32_e32 v198, v203, v198
	v_max_f32_e32 v203, v135, v135
	v_max_f32_e32 v203, v212, v203
	v_max3_f32 v203, v132, v133, v203
	v_max3_f32 v197, v197, v198, v203
	ds_bpermute_b32 v203, v199, v197
	v_exp_f32_e32 v198, v0
	v_sub_f32_e32 v164, v164, v200
	v_sub_f32_e32 v165, v165, v200
	v_sub_f32_e32 v166, v166, v200
	v_sub_f32_e32 v167, v167, v200
	v_sub_f32_e32 v144, v144, v200
	v_sub_f32_e32 v145, v145, v200
	s_waitcnt lgkmcnt(0)
	v_max_f32_e32 v0, v203, v203
	v_max_f32_e32 v0, v197, v0
	ds_bpermute_b32 v197, v195, v0
	v_sub_f32_e32 v146, v146, v200
	v_sub_f32_e32 v147, v147, v200
	v_mul_f32_e32 v58, v58, v198
	v_mul_f32_e32 v59, v59, v198
	v_mul_f32_e32 v56, v56, v198
	v_mul_f32_e32 v57, v57, v198
	v_exp_f32_e32 v170, v170
	s_waitcnt lgkmcnt(0)
; __device__ __forceinline__ void attn_item(const Params& p, int l, int hs, int idx) {
;     ...
;         const int i2 = (i + 2 < ntot) ? i + 2 : i;
	v_max3_f32 v0, v202, v0, v197
	v_sub_f32_e32 v197, v202, v0
	v_sub_f32_e32 v134, v134, v0
	v_sub_f32_e32 v135, v135, v0
	v_sub_f32_e32 v140, v140, v0
	v_sub_f32_e32 v141, v141, v0
	v_exp_f32_e32 v202, v134
	v_exp_f32_e32 v134, v197
	v_sub_f32_e32 v142, v142, v0
	v_sub_f32_e32 v143, v143, v0
	v_sub_f32_e32 v132, v132, v0
	v_sub_f32_e32 v133, v133, v0
	v_exp_f32_e32 v171, v171
	v_mul_f32_e32 v6, v6, v134
	v_mul_f32_e32 v7, v7, v134
	v_mul_f32_e32 v4, v4, v134
	v_mul_f32_e32 v5, v5, v134
	v_exp_f32_e32 v172, v172
	v_exp_f32_e32 v173, v173
	v_exp_f32_e32 v174, v174
	v_exp_f32_e32 v175, v175
	v_cvt_pk_bf16_f32 v208, v168, v169
	v_cvt_pk_bf16_f32 v209, v170, v171
	v_cvt_pk_bf16_f32 v210, v172, v173
	v_cvt_pk_bf16_f32 v211, v174, v175
	v_exp_f32_e32 v164, v164
	v_exp_f32_e32 v165, v165
	v_exp_f32_e32 v166, v166
	v_exp_f32_e32 v167, v167
	v_exp_f32_e32 v144, v144
	v_exp_f32_e32 v145, v145
	v_exp_f32_e32 v146, v146
	v_exp_f32_e32 v147, v147
	v_cvt_pk_bf16_f32 v212, v164, v165
	v_cvt_pk_bf16_f32 v213, v166, v167
	v_cvt_pk_bf16_f32 v214, v144, v145
	v_cvt_pk_bf16_f32 v215, v146, v147
	v_exp_f32_e32 v140, v140
	v_exp_f32_e32 v141, v141
	v_exp_f32_e32 v142, v142
	v_exp_f32_e32 v143, v143
	v_exp_f32_e32 v132, v132
	v_exp_f32_e32 v133, v133
	v_exp_f32_e32 v203, v135
	v_mfma_f32_16x16x32_bf16 v[96:99], v[84:87], v[208:211], v[96:99]
	v_cvt_pk_bf16_f32 v240, v140, v141
	v_cvt_pk_bf16_f32 v241, v142, v143
	v_cvt_pk_bf16_f32 v242, v132, v133
	v_mfma_f32_16x16x32_bf16 v[56:59], v[84:87], v[212:215], v[56:59]
	v_cvt_pk_bf16_f32 v243, v202, v203
	v_mul_f32_e64 v82, v82, v196
	v_mul_f32_e64 v83, v83, v196
	v_mul_f32_e32 v80, v80, v196
	v_mul_f32_e32 v81, v81, v196
	v_mfma_f32_16x16x32_bf16 v[4:7], v[84:87], v[240:243], v[4:7]
	v_mul_f32_e64 v86, v118, v194
	v_mul_f32_e64 v87, v119, v194
	v_mul_f32_e32 v84, v116, v194
	v_mul_f32_e32 v85, v117, v194
	v_mul_f32_e32 v54, v54, v198
	v_mul_f32_e32 v55, v55, v198
	v_mul_f32_e32 v52, v52, v198
	v_mul_f32_e32 v53, v53, v198
	v_mul_f32_e32 v10, v10, v134
	v_mul_f32_e32 v11, v11, v134
	v_mul_f32_e32 v8, v8, v134
	v_mul_f32_e32 v9, v9, v134
	v_mfma_f32_16x16x32_bf16 v[116:119], v[76:79], v[136:139], v[84:87]
	v_mul_f32_e64 v62, v62, v198
	v_mul_f32_e64 v63, v63, v198
	v_mul_f32_e32 v60, v60, v198
	v_mul_f32_e32 v61, v61, v198
	v_mul_f32_e32 v14, v14, v134
	v_mul_f32_e32 v15, v15, v134
	v_mfma_f32_16x16x32_bf16 v[80:83], v[76:79], v[208:211], v[80:83]
	v_mul_f32_e64 v12, v12, v134
	v_mul_f32_e64 v13, v13, v134
	v_mul_f32_e32 v66, v66, v198
	v_mul_f32_e32 v67, v67, v198
	v_mul_f32_e32 v64, v64, v198
	v_mul_f32_e32 v65, v65, v198
	v_mfma_f32_16x16x32_bf16 v[52:55], v[76:79], v[212:215], v[52:55]
	v_mul_f32_e64 v18, v18, v134
	v_mul_f32_e64 v19, v19, v134
	v_mul_f32_e32 v16, v16, v134
	v_mul_f32_e32 v17, v17, v134
	s_cselect_b32 s24, s45, s38
	v_mfma_f32_16x16x32_bf16 v[8:11], v[76:79], v[240:243], v[8:11]
	v_mul_f32_e64 v78, v122, v194
	v_mul_f32_e64 v79, v123, v194
	v_mul_f32_e32 v76, v120, v194
	v_mul_f32_e32 v77, v121, v194
	s_cmp_lt_i32 s24, s40
	v_mfma_f32_16x16x32_bf16 v[60:63], v[72:75], v[212:215], v[60:63]
	v_mfma_f32_16x16x32_bf16 v[120:123], v[72:75], v[136:139], v[76:79]
	s_nop 2
	v_mul_f32_e64 v78, v90, v196
	v_mul_f32_e64 v79, v91, v196
	v_mul_f32_e32 v76, v88, v196
	v_mul_f32_e32 v77, v89, v196
	v_mfma_f32_16x16x32_bf16 v[12:15], v[72:75], v[240:243], v[12:15]
	s_nop 0
	v_mfma_f32_16x16x32_bf16 v[88:91], v[72:75], v[208:211], v[76:79]
	v_mul_f32_e64 v74, v126, v194
	v_mul_f32_e64 v75, v127, v194
	v_mul_f32_e32 v72, v124, v194
	v_mul_f32_e32 v73, v125, v194
	v_mfma_f32_16x16x32_bf16 v[64:67], v[68:71], v[212:215], v[64:67]
	s_nop 0
	v_mfma_f32_16x16x32_bf16 v[124:127], v[68:71], v[136:139], v[72:75]
	s_nop 2
	v_mul_f32_e64 v74, v102, v196
	v_mul_f32_e64 v75, v103, v196
	v_mul_f32_e32 v72, v100, v196
	v_mul_f32_e32 v73, v101, v196
	v_mfma_f32_16x16x32_bf16 v[16:19], v[68:71], v[240:243], v[16:19]
	s_nop 0
	v_mfma_f32_16x16x32_bf16 v[100:103], v[68:71], v[208:211], v[72:75]
	s_cbranch_scc1 .LBB0_159
	s_sub_i32 s24, s24, s40
	s_mov_b64 s[6:7], 0x6020
	s_mov_b64 s[8:9], 0x6000
	s_mov_b64 s[10:11], 0x4020
	s_mov_b64 s[12:13], 0x4000
	s_mov_b64 s[16:17], 0x2020
	s_mov_b64 s[18:19], 0x2000
	s_mov_b64 s[22:23], s[84:85]
	s_mov_b64 s[20:21], s[0:1]
	v_mov_b64_e32 v[68:69], v[188:189]
	s_branch .LBB0_160

; __device__ __forceinline__ void attn_item(const Params& p, int l, int hs, int idx) {
;     ...
;         ATT_LOAD(i2, kfa, vla, vha);
.LBB0_160:
	s_lshl_b32 s25, s24, 6
	s_add_u32 s20, s20, s25
	v_add_f32_e32 v70, 0, v176
	v_add_f32_e32 v71, 0, v177
	v_add_f32_e32 v72, 0, v168
	v_add_f32_e32 v73, 0, v169
	s_addc_u32 s21, s21, 0
	v_add_f32_e32 v70, v178, v70
	v_add_f32_e32 v71, v179, v71
	v_add_f32_e32 v72, v170, v72
	v_add_f32_e32 v73, v171, v73
	s_add_u32 s18, s20, s18
	v_add_f32_e32 v70, v180, v70
	v_add_f32_e32 v71, v181, v71
	v_add_f32_e32 v72, v172, v72
	v_add_f32_e32 v73, v173, v73
	s_addc_u32 s19, s21, s19
	v_add_f32_e32 v70, v182, v70
	v_add_f32_e32 v71, v183, v71
	v_add_f32_e32 v72, v174, v72
	v_add_f32_e32 v73, v175, v73
	s_add_u32 s16, s20, s16
	v_mov_b32_e32 v74, v72
	v_mov_b32_e32 v75, v70
	v_mov_b32_e32 v70, v73
	s_addc_u32 s17, s21, s17
	v_mov_b32_e32 v197, v194
	v_add_f32_e32 v70, v74, v70
	v_add_f32_e32 v71, v75, v71
	s_add_u32 s12, s20, s12
	v_fma_f32 v2, v2, v196, v70
	v_fma_f32 v3, v3, v197, v71
	v_add_f32_e32 v70, 0, v164
	v_add_f32_e32 v71, 0, v165
	v_add_f32_e32 v72, 0, v140
	v_add_f32_e32 v73, 0, v141
	s_addc_u32 s13, s21, s13
	v_add_f32_e32 v70, v166, v70
	v_add_f32_e32 v71, v167, v71
	v_add_f32_e32 v72, v142, v72
	v_add_f32_e32 v73, v143, v73
	s_add_u32 s10, s20, s10
	v_add_f32_e32 v70, v144, v70
	v_add_f32_e32 v71, v145, v71
	v_add_f32_e32 v72, v132, v72
	v_add_f32_e32 v73, v133, v73
	s_addc_u32 s11, s21, s11
	v_add_f32_e32 v70, v146, v70
	v_add_f32_e32 v71, v147, v71
	v_add_f32_e32 v72, v202, v72
	v_add_f32_e32 v73, v203, v73
	s_add_u32 s8, s20, s8
	v_mov_b32_e32 v74, v72
	v_mov_b32_e32 v75, v70
	v_mov_b32_e32 v70, v73
	s_addc_u32 s9, s21, s9
	v_mov_b32_e32 v135, v198
	v_add_f32_e32 v70, v74, v70
	v_add_f32_e32 v71, v75, v71
	s_add_u32 s6, s20, s6
	v_fma_f32 v186, v186, v134, v70
	v_fma_f32 v187, v187, v135, v71
	v_lshl_add_u64 v[70:71], v[192:193], 0, s[22:23]
	s_addc_u32 s7, s21, s7
	v_mad_u64_u32 v[144:145], s[22:23], s24, v226, v[70:71]
	v_lshl_add_u64 v[72:73], s[20:21], 0, v[68:69]
	v_lshl_add_u64 v[76:77], s[18:19], 0, v[68:69]
	v_lshl_add_u64 v[70:71], s[16:17], 0, v[68:69]
	v_lshl_add_u64 v[132:133], s[12:13], 0, v[68:69]
	v_lshl_add_u64 v[74:75], s[10:11], 0, v[68:69]
	v_lshl_add_u64 v[134:135], s[8:9], 0, v[68:69]
	v_lshl_add_u64 v[68:69], s[6:7], 0, v[68:69]
	s_add_i32 m0, s28, 4096
	s_nop 0
	global_load_lds_dwordx4 v[72:73], off
	s_add_i32 m0, s28, 5120
	s_nop 0
	global_load_lds_dwordx4 v[76:77], off
	s_add_i32 m0, s28, 6144
	s_nop 0
	global_load_lds_dwordx4 v[132:133], off
	s_add_i32 m0, s28, 7168
	s_nop 0
	global_load_lds_dwordx4 v[134:135], off
	v_add_co_u32_e32 v136, vcc, 0xa000, v144
	s_nop 1
	v_addc_co_u32_e32 v137, vcc, 0, v145, vcc
	s_add_i32 m0, s28, -576
	s_nop 0
	global_load_lds_dwordx4 v[136:137], off offset:3648
	s_add_i32 m0, s28, -1536
	s_nop 0
	global_load_lds_dwordx4 v[136:137], off offset:3584
	s_add_i32 m0, s28, -2624
	s_nop 0
	global_load_lds_dwordx4 v[144:145], off offset:3648
	s_add_i32 m0, s28, -3584
	s_nop 0
	global_load_lds_dwordx4 v[144:145], off offset:3584
	s_andn2_b64 vcc, exec, s[34:35]
	s_cbranch_vccnz .LBB0_164
	s_waitcnt vmcnt(8)
	ds_read_b128 v[156:159], v216 offset:8192
	ds_read_b128 v[160:163], v216 offset:9216
	ds_read_b128 v[152:155], v216 offset:10240
	ds_read_b128 v[148:151], v216 offset:11264
	ds_read_b128 v[112:115], v216 offset:12288
	ds_read_b128 v[108:111], v216 offset:13312
	ds_read_b128 v[104:107], v216 offset:14336
	ds_read_b128 v[92:95], v216 offset:15360
	s_waitcnt lgkmcnt(4)
	v_mfma_f32_16x16x32_bf16 v[164:167], v[156:159], v[20:23], 0
	s_add_i32 s44, s44, -7
	s_cmp_lt_u32 s44, -4
	s_cselect_b64 s[6:7], -1, 0
	s_waitcnt vmcnt(10)
	v_mfma_f32_16x16x32_bf16 v[180:183], v[160:163], v[24:27], v[164:167]
	s_cmp_lt_u32 s42, s40
	s_cselect_b64 s[8:9], -1, 0
	s_and_b64 s[6:7], s[8:9], s[6:7]
	v_mfma_f32_16x16x32_bf16 v[164:167], v[156:159], v[28:31], 0
	s_andn2_b64 vcc, exec, s[6:7]
	v_mfma_f32_16x16x32_bf16 v[172:175], v[160:163], v[32:35], v[164:167]
	v_mfma_f32_16x16x32_bf16 v[164:167], v[156:159], v[36:39], 0
	v_mfma_f32_16x16x32_bf16 v[156:159], v[156:159], v[44:47], 0
	v_mfma_f32_16x16x32_bf16 v[168:171], v[160:163], v[40:43], v[164:167]
	v_mfma_f32_16x16x32_bf16 v[156:159], v[160:163], v[48:51], v[156:159]
	s_waitcnt vmcnt(9)
	v_mfma_f32_16x16x32_bf16 v[160:163], v[152:155], v[20:23], 0
	s_waitcnt vmcnt(8)
	v_mfma_f32_16x16x32_bf16 v[176:179], v[148:151], v[24:27], v[160:163]
	v_mfma_f32_16x16x32_bf16 v[160:163], v[152:155], v[28:31], 0
	v_mfma_f32_16x16x32_bf16 v[164:167], v[152:155], v[36:39], 0
	v_mfma_f32_16x16x32_bf16 v[152:155], v[152:155], v[44:47], 0
	v_mfma_f32_16x16x32_bf16 v[160:163], v[148:151], v[32:35], v[160:163]
	v_mfma_f32_16x16x32_bf16 v[164:167], v[148:151], v[40:43], v[164:167]
	v_mfma_f32_16x16x32_bf16 v[152:155], v[148:151], v[48:51], v[152:155]
	s_cbranch_vccnz .LBB0_163
	v_add_u32_e32 v148, 80, v207
	v_cmp_gt_u32_e64 s[6:7], s93, v148
	v_add_u32_e32 v148, 81, v207
	v_cmp_gt_u32_e64 s[8:9], s93, v148
	v_add_u32_e32 v148, 82, v207
	v_cmp_gt_u32_e64 s[10:11], s93, v148
	v_add_u32_e32 v148, 83, v207
	v_cmp_gt_u32_e64 s[12:13], s93, v148
	s_nop 1
	v_cndmask_b32_e64 v180, v180, v227, s[6:7]
	v_cndmask_b32_e64 v181, v181, v227, s[8:9]
	v_cndmask_b32_e64 v182, v182, v227, s[10:11]
	v_cndmask_b32_e64 v183, v183, v227, s[12:13]
	v_add_u32_e32 v148, 64, v207
	v_cmp_gt_u32_e64 s[6:7], s93, v148
	v_add_u32_e32 v148, 65, v207
	v_cmp_gt_u32_e64 s[8:9], s93, v148
	v_add_u32_e32 v148, 66, v207
	v_cmp_gt_u32_e64 s[10:11], s93, v148
	v_add_u32_e32 v148, 67, v207
	v_cmp_gt_u32_e64 s[12:13], s93, v148
	s_nop 1
	v_cndmask_b32_e64 v172, v172, v227, s[6:7]
	v_cndmask_b32_e64 v173, v173, v227, s[8:9]
	v_cndmask_b32_e64 v174, v174, v227, s[10:11]
	v_cndmask_b32_e64 v175, v175, v227, s[12:13]
	v_add_u32_e32 v148, 48, v207
	v_cmp_gt_u32_e64 s[6:7], s93, v148
	v_add_u32_e32 v148, 49, v207
	v_cmp_gt_u32_e64 s[8:9], s93, v148
	v_add_u32_e32 v148, 50, v207
	v_cmp_gt_u32_e64 s[10:11], s93, v148
	v_add_u32_e32 v148, 51, v207
	v_cmp_gt_u32_e64 s[12:13], s93, v148
	s_nop 1
	v_cndmask_b32_e64 v168, v168, v227, s[6:7]
	v_cndmask_b32_e64 v169, v169, v227, s[8:9]
	v_cndmask_b32_e64 v170, v170, v227, s[10:11]
	v_cndmask_b32_e64 v171, v171, v227, s[12:13]
	v_add_u32_e32 v148, 32, v207
	v_cmp_gt_u32_e64 s[6:7], s93, v148
	v_add_u32_e32 v148, 33, v207
	v_cmp_gt_u32_e64 s[8:9], s93, v148
	v_add_u32_e32 v148, 34, v207
	v_cmp_gt_u32_e64 s[10:11], s93, v148
	v_add_u32_e32 v148, 35, v207
	v_cmp_gt_u32_e64 s[12:13], s93, v148
	s_nop 1
	v_cndmask_b32_e64 v156, v156, v227, s[6:7]
	v_cndmask_b32_e64 v157, v157, v227, s[8:9]
	v_cndmask_b32_e64 v158, v158, v227, s[10:11]
	v_cndmask_b32_e64 v159, v159, v227, s[12:13]
	v_add_u32_e32 v148, 84, v207
	v_cmp_gt_u32_e64 s[6:7], s93, v148
	v_add_u32_e32 v148, 85, v207
	v_cmp_gt_u32_e64 s[8:9], s93, v148
	v_add_u32_e32 v148, 86, v207
	v_cmp_gt_u32_e64 s[10:11], s93, v148
	v_add_u32_e32 v148, 87, v207
	v_cmp_gt_u32_e64 s[12:13], s93, v148
	s_nop 1
	v_cndmask_b32_e64 v176, v176, v227, s[6:7]
	v_cndmask_b32_e64 v177, v177, v227, s[8:9]
	v_cndmask_b32_e64 v178, v178, v227, s[10:11]
	v_cndmask_b32_e64 v179, v179, v227, s[12:13]
	v_add_u32_e32 v148, 68, v207
	v_cmp_gt_u32_e64 s[6:7], s93, v148
	v_add_u32_e32 v148, 69, v207
	v_cmp_gt_u32_e64 s[8:9], s93, v148
	v_add_u32_e32 v148, 70, v207
	v_cmp_gt_u32_e64 s[10:11], s93, v148
	v_add_u32_e32 v148, 71, v207
	v_cmp_gt_u32_e64 s[12:13], s93, v148
	s_nop 1
	v_cndmask_b32_e64 v160, v160, v227, s[6:7]
	v_cndmask_b32_e64 v161, v161, v227, s[8:9]
	v_cndmask_b32_e64 v162, v162, v227, s[10:11]
	v_cndmask_b32_e64 v163, v163, v227, s[12:13]
	v_add_u32_e32 v148, 52, v207
	v_cmp_gt_u32_e64 s[6:7], s93, v148
	v_add_u32_e32 v148, 53, v207
	v_cmp_gt_u32_e64 s[8:9], s93, v148
	v_add_u32_e32 v148, 54, v207
	v_cmp_gt_u32_e64 s[10:11], s93, v148
	v_add_u32_e32 v148, 55, v207
	v_cmp_gt_u32_e64 s[12:13], s93, v148
	s_nop 1
	v_cndmask_b32_e64 v164, v164, v227, s[6:7]
	v_cndmask_b32_e64 v165, v165, v227, s[8:9]
	v_cndmask_b32_e64 v166, v166, v227, s[10:11]
	v_cndmask_b32_e64 v167, v167, v227, s[12:13]
	v_add_u32_e32 v148, 36, v207
	v_cmp_gt_u32_e64 s[6:7], s93, v148
	v_add_u32_e32 v148, 37, v207
	v_cmp_gt_u32_e64 s[8:9], s93, v148
	v_add_u32_e32 v148, 38, v207
	v_cmp_gt_u32_e64 s[10:11], s93, v148
	v_add_u32_e32 v148, 39, v207
	v_cmp_gt_u32_e64 s[12:13], s93, v148
	s_nop 1
	v_cndmask_b32_e64 v152, v152, v227, s[6:7]
	v_cndmask_b32_e64 v153, v153, v227, s[8:9]
	v_cndmask_b32_e64 v154, v154, v227, s[10:11]
	v_cndmask_b32_e64 v155, v155, v227, s[12:13]
.LBB0_163:
	v_max_f32_e32 v148, v181, v181
	v_max_f32_e32 v149, v180, v180
	v_max_f32_e32 v148, v149, v148
	v_max_f32_e32 v149, v183, v183
	v_max_f32_e32 v150, v182, v182
	v_max_f32_e32 v149, v150, v149
	v_max_f32_e32 v150, v179, v179
	v_max_f32_e32 v151, v178, v178
	v_max_f32_e32 v150, v151, v150
	v_max3_f32 v150, v176, v177, v150
	v_max3_f32 v148, v148, v149, v150
	ds_bpermute_b32 v149, v199, v148
	s_waitcnt lgkmcnt(0)
	v_max_f32_e32 v149, v149, v149
	v_max_f32_e32 v148, v148, v149
	ds_bpermute_b32 v149, v195, v148
	s_waitcnt lgkmcnt(0)
	v_max3_f32 v194, v206, v148, v149
	v_sub_f32_e32 v148, v180, v194
	v_sub_f32_e32 v149, v181, v194
	v_sub_f32_e32 v180, v182, v194
	v_sub_f32_e32 v181, v183, v194
	v_exp_f32_e32 v148, v148
	v_exp_f32_e32 v149, v149
	v_exp_f32_e32 v180, v180
	v_exp_f32_e32 v181, v181
	v_sub_f32_e32 v176, v176, v194
	v_sub_f32_e32 v177, v177, v194
	v_sub_f32_e32 v178, v178, v194
	v_sub_f32_e32 v179, v179, v194
	v_exp_f32_e32 v176, v176
	v_exp_f32_e32 v177, v177
	v_exp_f32_e32 v178, v178
	v_exp_f32_e32 v179, v179
	v_add_f32_e32 v150, 0, v148
	v_add_f32_e32 v151, 0, v149
	v_cvt_pk_bf16_f32 v148, v148, v149
	v_cvt_pk_bf16_f32 v149, v180, v181
	v_sub_f32_e32 v196, v206, v194
	v_add_f32_e32 v150, v180, v150
	v_add_f32_e32 v151, v181, v151
	v_exp_f32_e32 v198, v196
	v_add_f32_e32 v150, v176, v150
	v_add_f32_e32 v151, v177, v151
	v_mov_b32_e32 v181, v198
	v_add_f32_e32 v182, v178, v150
	v_add_f32_e32 v183, v179, v151
	v_cvt_pk_bf16_f32 v150, v176, v177
	v_max_f32_e32 v176, v173, v173
	v_max_f32_e32 v177, v172, v172
	v_cvt_pk_bf16_f32 v151, v178, v179
	v_max_f32_e32 v176, v177, v176
	v_max_f32_e32 v177, v175, v175
	v_max_f32_e32 v178, v174, v174
	v_max_f32_e32 v177, v178, v177
	v_max_f32_e32 v178, v163, v163
	v_max_f32_e32 v179, v162, v162
	v_max_f32_e32 v178, v179, v178
	v_max3_f32 v178, v160, v161, v178
	v_max3_f32 v176, v176, v177, v178
	ds_bpermute_b32 v177, v199, v176
	v_mul_f32_e32 v130, v130, v198
	v_mul_f32_e32 v131, v131, v198
	v_mul_f32_e32 v128, v128, v198
	v_mul_f32_e32 v129, v129, v198
	v_mul_f32_e32 v118, v118, v198
	v_mul_f32_e32 v119, v119, v198
	v_mul_f32_e32 v116, v116, v198
	v_mul_f32_e32 v117, v117, v198
	s_waitcnt lgkmcnt(0)
	v_max_f32_e32 v177, v177, v177
	v_max_f32_e32 v176, v176, v177
	ds_bpermute_b32 v177, v195, v176
	v_mul_f32_e32 v122, v122, v198
	v_mul_f32_e32 v123, v123, v198
	v_mul_f32_e32 v120, v120, v198
	v_mul_f32_e32 v121, v121, v198
	v_mul_f32_e32 v126, v126, v198
	v_mul_f32_e32 v127, v127, v198
	v_mul_f32_e32 v124, v124, v198
	v_mul_f32_e32 v125, v125, v198
	s_waitcnt lgkmcnt(0)
	v_max3_f32 v196, v204, v176, v177
	v_sub_f32_e32 v172, v172, v196
	v_sub_f32_e32 v173, v173, v196
	v_sub_f32_e32 v174, v174, v196
	v_sub_f32_e32 v175, v175, v196
	v_exp_f32_e32 v172, v172
	v_exp_f32_e32 v173, v173
	v_exp_f32_e32 v174, v174
	v_exp_f32_e32 v175, v175
	v_sub_f32_e32 v160, v160, v196
	v_sub_f32_e32 v161, v161, v196
	v_add_f32_e32 v176, 0, v172
	v_add_f32_e32 v177, 0, v173
	v_exp_f32_e32 v178, v160
	v_exp_f32_e32 v179, v161
	v_add_f32_e32 v176, v174, v176
	v_add_f32_e32 v177, v175, v177
	v_sub_f32_e32 v162, v162, v196
	v_sub_f32_e32 v163, v163, v196
	v_sub_f32_e32 v180, v204, v196
	v_add_f32_e32 v160, v178, v176
	v_add_f32_e32 v161, v179, v177
	v_exp_f32_e32 v176, v162
	v_exp_f32_e32 v177, v163
	v_exp_f32_e32 v180, v180
	v_mov_b32_e32 v163, v182
	v_mfma_f32_16x16x32_bf16 v[128:131], v[112:115], v[148:151], v[128:131]
	v_add_f32_e64 v160, v176, v160
	v_add_f32_e64 v161, v177, v161
	v_mul_f32_e32 v98, v98, v180
	v_mul_f32_e32 v99, v99, v180
	v_mov_b32_e32 v162, v160
	v_mov_b32_e32 v182, v161
	v_add_f32_e32 v160, v162, v182
	v_add_f32_e32 v161, v163, v183
	v_mul_f32_e32 v96, v96, v180
	v_mul_f32_e32 v97, v97, v180
	v_fma_f32 v2, v2, v180, v160
	v_fma_f32 v3, v3, v181, v161
	v_cvt_pk_bf16_f32 v160, v172, v173
	v_max_f32_e32 v172, v169, v169
	v_max_f32_e32 v173, v168, v168
	v_cvt_pk_bf16_f32 v161, v174, v175
	v_max_f32_e32 v172, v173, v172
	v_max_f32_e32 v173, v171, v171
	v_max_f32_e32 v174, v170, v170
	v_max_f32_e32 v173, v174, v173
	v_max_f32_e32 v174, v167, v167
	v_max_f32_e32 v175, v166, v166
	v_max_f32_e32 v174, v175, v174
	v_max3_f32 v174, v164, v165, v174
	v_max3_f32 v172, v172, v173, v174
	ds_bpermute_b32 v173, v199, v172
	v_cvt_pk_bf16_f32 v162, v178, v179
	v_cvt_pk_bf16_f32 v163, v176, v177
	v_mul_f32_e32 v82, v82, v180
	v_mul_f32_e32 v83, v83, v180
	v_mul_f32_e32 v80, v80, v180
	v_mul_f32_e32 v81, v81, v180
	s_waitcnt lgkmcnt(0)
	v_max_f32_e32 v173, v173, v173
	v_max_f32_e32 v172, v172, v173
	ds_bpermute_b32 v173, v195, v172
	v_mul_f32_e32 v90, v90, v180
	v_mul_f32_e32 v91, v91, v180
	v_mul_f32_e32 v88, v88, v180
	v_mul_f32_e32 v89, v89, v180
	v_mul_f32_e32 v102, v102, v180
	v_mul_f32_e32 v103, v103, v180
	v_mul_f32_e32 v100, v100, v180
	v_mul_f32_e32 v101, v101, v180
	s_waitcnt lgkmcnt(0)
	v_max3_f32 v198, v200, v172, v173
	v_sub_f32_e32 v168, v168, v198
	v_sub_f32_e32 v169, v169, v198
	v_sub_f32_e32 v170, v170, v198
	v_sub_f32_e32 v171, v171, v198
	v_exp_f32_e32 v168, v168
	v_exp_f32_e32 v169, v169
	v_exp_f32_e32 v170, v170
	v_exp_f32_e32 v171, v171
	v_sub_f32_e32 v164, v164, v198
	v_sub_f32_e32 v165, v165, v198
	v_add_f32_e32 v172, 0, v168
	v_add_f32_e32 v173, 0, v169
	v_exp_f32_e32 v174, v164
	v_exp_f32_e32 v175, v165
	v_add_f32_e32 v172, v170, v172
	v_add_f32_e32 v173, v171, v173
	v_sub_f32_e32 v166, v166, v198
	v_sub_f32_e32 v167, v167, v198
	v_sub_f32_e32 v178, v200, v198
	v_add_f32_e32 v164, v174, v172
	v_add_f32_e32 v165, v175, v173
	v_exp_f32_e32 v172, v166
	v_exp_f32_e32 v173, v167
	v_exp_f32_e32 v178, v178
	v_mfma_f32_16x16x32_bf16 v[96:99], v[112:115], v[160:163], v[96:99]
	v_add_f32_e64 v176, v172, v164
	v_add_f32_e64 v177, v173, v165
	v_cvt_pk_bf16_f32 v164, v168, v169
	v_max_f32_e32 v168, v157, v157
	v_max_f32_e32 v169, v156, v156
	v_cvt_pk_bf16_f32 v165, v170, v171
	v_max_f32_e32 v168, v169, v168
	v_max_f32_e32 v169, v159, v159
	v_max_f32_e32 v170, v158, v158
	v_max_f32_e32 v169, v170, v169
	v_max_f32_e32 v170, v155, v155
	v_max_f32_e32 v171, v154, v154
	v_max_f32_e32 v170, v171, v170
	v_max3_f32 v170, v152, v153, v170
	v_max3_f32 v168, v168, v169, v170
	ds_bpermute_b32 v169, v199, v168
	v_cvt_pk_bf16_f32 v166, v174, v175
	v_cvt_pk_bf16_f32 v167, v172, v173
	v_mov_b32_e32 v173, v178
	v_mul_f32_e32 v58, v58, v178
	v_mul_f32_e32 v59, v59, v178
	s_waitcnt lgkmcnt(0)
; __device__ __forceinline__ void attn_item(const Params& p, int l, int hs, int idx) {
;     ...
;     for (int i = 0; i < ntot; i += 2) {
;         const int i1 = (i + 1 < ntot) ? i + 1 : i;
;         ATT_LOAD(i1, kfb, vlb, vhb);
;         ATT_COMPUTE(i, kfa, vla, vha);
;         const int i2 = (i + 2 < ntot) ? i + 2 : i;
;         ATT_LOAD(i2, kfa, vla, vha);
;         if (i + 1 < ntot) ATT_COMPUTE(i + 1, kfb, vlb, vhb);
;     }
	v_max_f32_e32 v169, v169, v169
	v_max_f32_e32 v168, v168, v169
	ds_bpermute_b32 v169, v195, v168
	v_mul_f32_e32 v56, v56, v178
	v_mul_f32_e32 v57, v57, v178
	v_mul_f32_e32 v54, v54, v178
	v_mul_f32_e32 v55, v55, v178
	v_mul_f32_e32 v52, v52, v178
	v_mul_f32_e32 v53, v53, v178
	v_mul_f32_e32 v62, v62, v178
	v_mul_f32_e32 v63, v63, v178
	s_waitcnt lgkmcnt(0)
	v_max3_f32 v202, v0, v168, v169
	v_sub_f32_e32 v156, v156, v202
	v_sub_f32_e32 v157, v157, v202
	v_sub_f32_e32 v158, v158, v202
	v_sub_f32_e32 v159, v159, v202
	v_exp_f32_e32 v156, v156
	v_exp_f32_e32 v157, v157
	v_exp_f32_e32 v158, v158
	v_exp_f32_e32 v159, v159
	v_sub_f32_e32 v152, v152, v202
	v_sub_f32_e32 v153, v153, v202
	v_add_f32_e32 v168, 0, v156
	v_add_f32_e32 v169, 0, v157
	v_exp_f32_e32 v170, v152
	v_exp_f32_e32 v171, v153
	v_add_f32_e32 v168, v158, v168
	v_add_f32_e32 v169, v159, v169
	v_sub_f32_e32 v154, v154, v202
	v_sub_f32_e32 v155, v155, v202
	v_sub_f32_e32 v0, v0, v202
	v_add_f32_e32 v152, v170, v168
	v_add_f32_e32 v153, v171, v169
	v_exp_f32_e32 v168, v154
	v_exp_f32_e32 v169, v155
	v_exp_f32_e32 v172, v0
	v_mov_b32_e32 v155, v176
	v_mul_f32_e32 v60, v60, v178
	v_mul_f32_e32 v61, v61, v178
	v_add_f32_e32 v152, v168, v152
	v_add_f32_e32 v153, v169, v153
	v_mul_f32_e32 v66, v66, v178
	v_mul_f32_e32 v67, v67, v178
	v_mov_b32_e32 v154, v152
	v_mov_b32_e32 v176, v153
	v_mul_f32_e32 v64, v64, v178
	v_mul_f32_e32 v65, v65, v178
	v_add_f32_e32 v152, v154, v176
	v_add_f32_e32 v153, v155, v177
	v_mul_f32_e32 v6, v6, v172
	v_mul_f32_e32 v7, v7, v172
	v_mul_f32_e32 v4, v4, v172
	v_mul_f32_e32 v5, v5, v172
	v_mul_f32_e32 v10, v10, v172
	v_mul_f32_e32 v11, v11, v172
	v_mul_f32_e32 v8, v8, v172
	v_mul_f32_e32 v9, v9, v172
	v_mul_f32_e32 v14, v14, v172
	v_mul_f32_e32 v15, v15, v172
	v_mul_f32_e32 v12, v12, v172
	v_mul_f32_e32 v13, v13, v172
	v_mul_f32_e32 v18, v18, v172
	v_mul_f32_e32 v19, v19, v172
	v_mul_f32_e32 v16, v16, v172
	v_mul_f32_e32 v17, v17, v172
	v_fma_f32 v186, v186, v172, v152
	v_fma_f32 v187, v187, v173, v153
	v_cvt_pk_bf16_f32 v152, v156, v157
	v_cvt_pk_bf16_f32 v153, v158, v159
	v_cvt_pk_bf16_f32 v154, v170, v171
	v_cvt_pk_bf16_f32 v155, v168, v169
	v_mfma_f32_16x16x32_bf16 v[56:59], v[112:115], v[164:167], v[56:59]
	s_nop 0
	v_mfma_f32_16x16x32_bf16 v[4:7], v[112:115], v[152:155], v[4:7]
	v_mfma_f32_16x16x32_bf16 v[116:119], v[108:111], v[148:151], v[116:119]
	v_mfma_f32_16x16x32_bf16 v[80:83], v[108:111], v[160:163], v[80:83]
	v_mfma_f32_16x16x32_bf16 v[52:55], v[108:111], v[164:167], v[52:55]
	v_mfma_f32_16x16x32_bf16 v[8:11], v[108:111], v[152:155], v[8:11]
	v_mfma_f32_16x16x32_bf16 v[120:123], v[104:107], v[148:151], v[120:123]
	v_mfma_f32_16x16x32_bf16 v[88:91], v[104:107], v[160:163], v[88:91]
	v_mfma_f32_16x16x32_bf16 v[60:63], v[104:107], v[164:167], v[60:63]
	v_mfma_f32_16x16x32_bf16 v[12:15], v[104:107], v[152:155], v[12:15]
	v_mfma_f32_16x16x32_bf16 v[124:127], v[92:95], v[148:151], v[124:127]
	v_mfma_f32_16x16x32_bf16 v[100:103], v[92:95], v[160:163], v[100:103]
	v_mfma_f32_16x16x32_bf16 v[64:67], v[92:95], v[164:167], v[64:67]
	v_mfma_f32_16x16x32_bf16 v[16:19], v[92:95], v[152:155], v[16:19]
	s_andn2_b64 vcc, exec, s[96:97]
	s_cbranch_vccnz .LBB0_165
	s_branch .LBB0_139
